# grid barrier: non-leader workgroups poll the cross-XCD generation word directly (per-XCD relay hop removed)
# speedup vs baseline: 1.0017x; 1.0017x over previous
.LBB0_188:
	s_or_b64 exec, exec, s[10:11]
	v_cvt_f32_u32_e32 v7, v4
	s_waitcnt vmcnt(0)
	v_readfirstlane_b32 s10, v5
	v_sub_u32_e32 v5, 0, v4
	v_rcp_iflag_f32_e32 v7, v7
	v_add_u32_e32 v8, s10, v1
	v_mul_f32_e32 v7, 0x4f7ffffe, v7
	v_cvt_u32_f32_e32 v7, v7
	v_mul_lo_u32 v1, v5, v7
	v_mul_hi_u32 v1, v7, v1
	v_add_u32_e32 v1, v7, v1
	v_mul_hi_u32 v1, v8, v1
	v_mul_lo_u32 v5, v1, v4
	v_sub_u32_e32 v5, v8, v5
	v_add_u32_e32 v7, 1, v1
	v_cmp_ge_u32_e32 vcc, v5, v4
	s_nop 1
	v_cndmask_b32_e32 v1, v1, v7, vcc
	v_sub_u32_e32 v7, v5, v4
	v_cndmask_b32_e32 v5, v5, v7, vcc
	v_add_u32_e32 v7, 1, v1
	v_cmp_ge_u32_e32 vcc, v5, v4
	v_add_u32_e32 v5, 1, v8
	s_nop 0
	v_cndmask_b32_e32 v1, v1, v7, vcc
	v_mul_lo_u32 v7, v4, v1
	v_add_u32_e32 v4, v7, v4
	v_cmp_ne_u32_e32 vcc, v5, v4
	s_and_saveexec_b64 s[10:11], vcc
	s_xor_b64 s[10:11], exec, s[10:11]
	s_cbranch_execz .LBB0_202
	v_readlane_b32 s12, v252, 1
	v_readlane_b32 s13, v252, 2
	s_waitcnt lgkmcnt(0)
	s_nop 3
	global_load_dword v2, v3, s[12:13] sc1
	s_waitcnt vmcnt(0)
	v_cmp_eq_u32_e32 vcc, v2, v1
	s_and_saveexec_b64 s[12:13], vcc
	s_cbranch_execz .LBB0_201
	s_mov_b32 s25, 1
	s_mov_b64 s[14:15], 0
	s_branch .LBB0_192

.LBB0_219:
	s_or_b64 exec, exec, s[10:11]
	s_mov_b64 s[10:11], exec
	v_mbcnt_lo_u32_b32 v1, s10, 0
	v_mbcnt_hi_u32_b32 v1, s11, v1
	v_cmp_eq_u32_e32 vcc, 0, v1
	s_waitcnt vmcnt(0)
	buffer_inv sc1
	s_and_saveexec_b64 s[12:13], vcc
	s_cbranch_execz .LBB0_221
	s_bcnt1_i32_b64 s10, s[10:11]
	v_mov_b32_e32 v1, s10
	v_readlane_b32 s10, v251, 50
	v_readlane_b32 s11, v251, 51
	s_nop 4
	s_nop 0

.LBB0_296:
	s_or_b64 exec, exec, s[12:13]
	v_cvt_f32_u32_e32 v7, v4
	s_waitcnt vmcnt(0)
	v_readfirstlane_b32 s12, v5
	v_sub_u32_e32 v5, 0, v4
	v_rcp_iflag_f32_e32 v7, v7
	v_add_u32_e32 v8, s12, v1
	v_mul_f32_e32 v7, 0x4f7ffffe, v7
	v_cvt_u32_f32_e32 v7, v7
	v_mul_lo_u32 v1, v5, v7
	v_mul_hi_u32 v1, v7, v1
	v_add_u32_e32 v1, v7, v1
	v_mul_hi_u32 v1, v8, v1
	v_mul_lo_u32 v5, v1, v4
	v_sub_u32_e32 v5, v8, v5
	v_add_u32_e32 v7, 1, v1
	v_cmp_ge_u32_e32 vcc, v5, v4
	s_nop 1
	v_cndmask_b32_e32 v1, v1, v7, vcc
	v_sub_u32_e32 v7, v5, v4
	v_cndmask_b32_e32 v5, v5, v7, vcc
	v_add_u32_e32 v7, 1, v1
	v_cmp_ge_u32_e32 vcc, v5, v4
	v_add_u32_e32 v5, 1, v8
	s_nop 0
	v_cndmask_b32_e32 v1, v1, v7, vcc
	v_mul_lo_u32 v7, v4, v1
	v_add_u32_e32 v4, v7, v4
	v_cmp_ne_u32_e32 vcc, v5, v4
	s_and_saveexec_b64 s[12:13], vcc
	s_xor_b64 s[12:13], exec, s[12:13]
	s_cbranch_execz .LBB0_310
	v_readlane_b32 s14, v252, 1
	v_readlane_b32 s15, v252, 2
	s_waitcnt lgkmcnt(0)
	s_nop 3
	global_load_dword v2, v3, s[14:15] sc1
	s_waitcnt vmcnt(0)
	v_cmp_eq_u32_e32 vcc, v2, v1
	s_and_saveexec_b64 s[14:15], vcc
	s_cbranch_execz .LBB0_309
	s_mov_b32 s26, 1
	s_mov_b64 s[16:17], 0
	s_branch .LBB0_300

.LBB0_327:
	s_or_b64 exec, exec, s[12:13]
	s_mov_b64 s[12:13], exec
	v_mbcnt_lo_u32_b32 v1, s12, 0
	v_mbcnt_hi_u32_b32 v1, s13, v1
	v_cmp_eq_u32_e32 vcc, 0, v1
	s_waitcnt vmcnt(0)
	buffer_inv sc1
	s_and_saveexec_b64 s[14:15], vcc
	s_cbranch_execz .LBB0_329
	s_bcnt1_i32_b64 s12, s[12:13]
	v_mov_b32_e32 v1, s12
	v_readlane_b32 s12, v251, 50
	v_readlane_b32 s13, v251, 51
	s_nop 4
	s_nop 0

.LBB0_940:
	s_or_b64 exec, exec, s[8:9]
	v_cvt_f32_u32_e32 v7, v4
	s_waitcnt vmcnt(0)
	v_readfirstlane_b32 s8, v5
	v_sub_u32_e32 v5, 0, v4
	v_rcp_iflag_f32_e32 v7, v7
	v_add_u32_e32 v8, s8, v1
	v_mul_f32_e32 v7, 0x4f7ffffe, v7
	v_cvt_u32_f32_e32 v7, v7
	v_mul_lo_u32 v1, v5, v7
	v_mul_hi_u32 v1, v7, v1
	v_add_u32_e32 v1, v7, v1
	v_mul_hi_u32 v1, v8, v1
	v_mul_lo_u32 v5, v1, v4
	v_sub_u32_e32 v5, v8, v5
	v_add_u32_e32 v7, 1, v1
	v_cmp_ge_u32_e32 vcc, v5, v4
	s_nop 1
	v_cndmask_b32_e32 v1, v1, v7, vcc
	v_sub_u32_e32 v7, v5, v4
	v_cndmask_b32_e32 v5, v5, v7, vcc
	v_add_u32_e32 v7, 1, v1
	v_cmp_ge_u32_e32 vcc, v5, v4
	v_add_u32_e32 v5, 1, v8
	s_nop 0
	v_cndmask_b32_e32 v1, v1, v7, vcc
	v_mul_lo_u32 v7, v4, v1
	v_add_u32_e32 v4, v7, v4
	v_cmp_ne_u32_e32 vcc, v5, v4
	s_and_saveexec_b64 s[8:9], vcc
	s_xor_b64 s[8:9], exec, s[8:9]
	s_cbranch_execz .LBB0_954
	v_readlane_b32 s10, v252, 1
	v_readlane_b32 s11, v252, 2
	s_waitcnt lgkmcnt(0)
	s_nop 3
	global_load_dword v2, v3, s[10:11] sc1
	s_waitcnt vmcnt(0)
	v_cmp_eq_u32_e32 vcc, v2, v1
	s_and_saveexec_b64 s[10:11], vcc
	s_cbranch_execz .LBB0_953
	s_mov_b32 s22, 1
	s_mov_b64 s[12:13], 0
	s_branch .LBB0_944

.LBB0_971:
	s_or_b64 exec, exec, s[8:9]
	s_mov_b64 s[8:9], exec
	v_mbcnt_lo_u32_b32 v1, s8, 0
	v_mbcnt_hi_u32_b32 v1, s9, v1
	v_cmp_eq_u32_e32 vcc, 0, v1
	s_waitcnt vmcnt(0)
	buffer_inv sc1
	s_and_saveexec_b64 s[10:11], vcc
	s_cbranch_execz .LBB0_973
	s_bcnt1_i32_b64 s8, s[8:9]
	v_mov_b32_e32 v1, s8
	v_readlane_b32 s8, v251, 50
	v_readlane_b32 s9, v251, 51
	s_nop 4
	s_nop 0

.LBB0_1508:
	s_or_b64 exec, exec, s[10:11]
	v_cvt_f32_u32_e32 v7, v4
	s_waitcnt vmcnt(0)
	v_readfirstlane_b32 s10, v5
	v_sub_u32_e32 v5, 0, v4
	v_rcp_iflag_f32_e32 v7, v7
	v_add_u32_e32 v8, s10, v1
	v_mul_f32_e32 v7, 0x4f7ffffe, v7
	v_cvt_u32_f32_e32 v7, v7
	v_mul_lo_u32 v1, v5, v7
	v_mul_hi_u32 v1, v7, v1
	v_add_u32_e32 v1, v7, v1
	v_mul_hi_u32 v1, v8, v1
	v_mul_lo_u32 v5, v1, v4
	v_sub_u32_e32 v5, v8, v5
	v_add_u32_e32 v7, 1, v1
	v_cmp_ge_u32_e32 vcc, v5, v4
	s_nop 1
	v_cndmask_b32_e32 v1, v1, v7, vcc
	v_sub_u32_e32 v7, v5, v4
	v_cndmask_b32_e32 v5, v5, v7, vcc
	v_add_u32_e32 v7, 1, v1
	v_cmp_ge_u32_e32 vcc, v5, v4
	v_add_u32_e32 v5, 1, v8
	s_nop 0
	v_cndmask_b32_e32 v1, v1, v7, vcc
	v_mul_lo_u32 v7, v4, v1
	v_add_u32_e32 v4, v7, v4
	v_cmp_ne_u32_e32 vcc, v5, v4
	s_and_saveexec_b64 s[10:11], vcc
	s_xor_b64 s[10:11], exec, s[10:11]
	s_cbranch_execz .LBB0_1522
	v_readlane_b32 s12, v252, 1
	v_readlane_b32 s13, v252, 2
	s_waitcnt lgkmcnt(0)
	s_nop 3
	global_load_dword v2, v3, s[12:13] sc1
	s_waitcnt vmcnt(0)
	v_cmp_eq_u32_e32 vcc, v2, v1
	s_and_saveexec_b64 s[12:13], vcc
	s_cbranch_execz .LBB0_1521
	s_mov_b32 s24, 1
	s_mov_b64 s[14:15], 0
	s_branch .LBB0_1512

.LBB0_1540:
	s_bcnt1_i32_b64 s10, s[10:11]
	v_mov_b32_e32 v1, s10
	v_readlane_b32 s10, v251, 50
	v_readlane_b32 s11, v251, 51
	s_nop 4
	s_nop 0
	s_getpc_b64 s[98:99]
